# mixer m3: attention QK and retention K/T fragments prefetched one block ahead of their MFMAs (LDS reads batched into spare registers)
# speedup vs baseline: 1.0023x; 1.0023x over previous
; __device__ __forceinline__ float log_sigmoid(float x) { return -log1pf(expf(-x)); }
; __device__ __forceinline__ void m3_outputs(const KQ p_in, int e, bool ctx_full, unsigned char* smem, unsigned* scan_word) {
;     ...
;             const float lgf = log_sigmoid(dec[h]), lgb = log_sigmoid(dec[8 + h]);
.LBB0_960:
	v_add_u32_e32 v106, s7, v81
	s_bfe_u32 s6, s2, 0x30003
	s_mov_b64 s[0:1], -1
	s_andn2_b64 vcc, exec, s[36:37]
	v_ashrrev_i32_e32 v107, 31, v106
	v_lshlrev_b32_e32 v144, 1, v84
	s_cbranch_vccnz .LBB0_962
	s_lshl_b32 s0, s6, 2
	s_add_u32 s0, s73, s0
	s_addc_u32 s1, s64, 0
	v_mov_b64_e32 v[0:1], s[0:1]
	global_load_dword v2, v[0:1], off
	s_mov_b32 s0, 0xc2b17218
	global_load_dword v0, v[0:1], off offset:32
	s_mov_b32 s11, 0x3f2aaaab
	s_mov_b32 s12, 0x3f317218
	s_mov_b32 s1, 0x7f800000
	s_mov_b32 s10, 0x33800000
	s_lshl_b32 s80, s6, 7
	s_waitcnt lgkmcnt(0)
	s_barrier
	s_waitcnt vmcnt(2)
	s_waitcnt vmcnt(1)
	v_mul_f32_e32 v3, 0xbfb8aa3b, v2
	v_fma_f32 v4, v2, s42, -v3
	v_rndne_f32_e32 v5, v3
	v_fmac_f32_e32 v4, 0xb2a5705f, v2
	v_sub_f32_e32 v3, v3, v5
	v_add_f32_e32 v3, v3, v4
	v_exp_f32_e32 v3, v3
	v_cvt_i32_f32_e32 v4, v5
	v_cmp_nlt_f32_e32 vcc, s9, v2
	s_waitcnt vmcnt(0)
	v_mul_f32_e32 v1, 0xbfb8aa3b, v0
	v_ldexp_f32 v3, v3, v4
	v_cndmask_b32_e32 v3, 0, v3, vcc
	v_cmp_ngt_f32_e32 vcc, s0, v2
	s_nop 1
	v_cndmask_b32_e32 v16, v203, v3, vcc
	v_add_f32_e32 v4, 1.0, v16
	v_add_f32_e32 v2, -1.0, v4
	v_sub_f32_e32 v3, v2, v4
	v_add_f32_e32 v3, 1.0, v3
	v_sub_f32_e32 v2, v16, v2
	v_add_f32_e32 v5, v2, v3
	v_frexp_mant_f32_e32 v2, v4
	v_cmp_gt_f32_e32 vcc, s11, v2
	v_cvt_f64_f32_e32 v[2:3], v4
	v_frexp_exp_i32_f64_e32 v2, v[2:3]
	v_subbrev_co_u32_e32 v10, vcc, 0, v2, vcc
	v_sub_u32_e32 v2, 0, v10
	v_ldexp_f32 v3, v4, v2
	v_add_f32_e32 v4, -1.0, v3
	v_add_f32_e32 v6, 1.0, v3
	v_ldexp_f32 v2, v5, v2
	v_add_f32_e32 v5, 1.0, v4
	v_add_f32_e32 v7, -1.0, v6
	v_sub_f32_e32 v5, v3, v5
	v_sub_f32_e32 v3, v3, v7
	v_add_f32_e32 v5, v2, v5
	v_add_f32_e32 v2, v2, v3
	v_add_f32_e32 v11, v6, v2
	v_rcp_f32_e32 v13, v11
	v_sub_f32_e32 v3, v6, v11
	v_add_f32_e32 v12, v2, v3
	v_add_f32_e32 v3, v4, v5
	v_mul_f32_e32 v15, v3, v13
	v_sub_f32_e32 v2, v4, v3
	v_mul_f32_e32 v4, v11, v15
	v_fma_f32 v6, v15, v11, -v4
	v_fmac_f32_e32 v6, v15, v12
	v_add_f32_e32 v14, v5, v2
	v_add_f32_e32 v2, v4, v6
	v_sub_f32_e32 v5, v3, v2
	v_pk_add_f32 v[8:9], v[2:3], v[4:5] neg_lo:[0,1] neg_hi:[0,1]
	v_mov_b32_e32 v7, v2
	v_pk_add_f32 v[2:3], v[8:9], v[6:7] neg_lo:[0,1] neg_hi:[0,1]
	v_cmp_neq_f32_e32 vcc, s1, v16
	v_add_f32_e32 v3, v14, v3
	v_add_f32_e32 v2, v2, v3
	v_add_f32_e32 v3, v5, v2
	v_mul_f32_e32 v14, v13, v3
	v_mul_f32_e32 v4, v11, v14
	v_fma_f32 v6, v14, v11, -v4
	v_fmac_f32_e32 v6, v14, v12
	v_sub_f32_e32 v5, v5, v3
	v_add_f32_e32 v11, v2, v5
	v_add_f32_e32 v2, v4, v6
	v_sub_f32_e32 v5, v3, v2
	v_pk_add_f32 v[8:9], v[2:3], v[4:5] neg_lo:[0,1] neg_hi:[0,1]
	v_mov_b32_e32 v7, v2
	v_pk_add_f32 v[2:3], v[8:9], v[6:7] neg_lo:[0,1] neg_hi:[0,1]
	s_nop 0
	v_add_f32_e32 v3, v11, v3
	v_add_f32_e32 v2, v2, v3
	v_add_f32_e32 v3, v15, v14
	v_add_f32_e32 v2, v5, v2
	v_sub_f32_e32 v4, v3, v15
	v_mul_f32_e32 v2, v13, v2
	v_sub_f32_e32 v4, v14, v4
	v_add_f32_e32 v4, v4, v2
	v_add_f32_e32 v6, v3, v4
	v_mul_f32_e32 v7, v6, v6
	v_fmamk_f32 v2, v7, 0x3e9b6dac, v191
	v_fmaak_f32 v149, v7, v2, 0x3f2aaada
	v_cvt_f32_i32_e32 v2, v10
	v_sub_f32_e32 v3, v6, v3
	v_sub_f32_e32 v3, v4, v3
	v_ldexp_f32 v8, v3, 1
	v_mul_f32_e32 v3, v6, v7
	v_ldexp_f32 v5, v6, 1
	v_pk_mul_f32 v[6:7], v[2:3], v[148:149]
	s_nop 0
	v_fma_f32 v4, v2, s12, -v6
	v_fmac_f32_e32 v4, 0xb102e308, v2
	v_pk_add_f32 v[2:3], v[6:7], v[4:5]
	s_nop 0
	v_sub_f32_e32 v5, v3, v5
	v_sub_f32_e32 v5, v7, v5
	v_add_f32_e32 v9, v8, v5
	v_mov_b32_e32 v8, v6
	v_pk_add_f32 v[6:7], v[2:3], v[6:7] neg_lo:[0,1] neg_hi:[0,1]
	v_pk_add_f32 v[10:11], v[2:3], v[8:9]
	v_mov_b32_e32 v5, v2
	v_mov_b32_e32 v7, v11
	v_pk_add_f32 v[12:13], v[4:5], v[6:7] neg_lo:[0,1] neg_hi:[0,1]
	v_pk_add_f32 v[4:5], v[4:5], v[6:7]
	v_mov_b32_e32 v8, v9
	v_pk_add_f32 v[6:7], v[4:5], v[2:3] op_sel:[1,0] op_sel_hi:[0,1] neg_lo:[0,1] neg_hi:[0,1]
	v_pk_add_f32 v[14:15], v[10:11], v[6:7] op_sel_hi:[1,0] neg_lo:[0,1] neg_hi:[0,1]
	v_mov_b32_e32 v10, v11
	v_mov_b32_e32 v11, v5
	v_pk_mov_b32 v[6:7], v[2:3], v[6:7] op_sel:[1,0]
	v_mov_b32_e32 v9, v2
	v_pk_add_f32 v[6:7], v[10:11], v[6:7] neg_lo:[0,1] neg_hi:[0,1]
	v_mov_b32_e32 v14, v12
	v_pk_add_f32 v[2:3], v[8:9], v[6:7] neg_lo:[0,1] neg_hi:[0,1]
	v_mov_b32_e32 v13, v5
	v_pk_add_f32 v[6:7], v[14:15], v[2:3]
	s_nop 0
	v_pk_add_f32 v[8:9], v[6:7], v[6:7] op_sel:[0,1] op_sel_hi:[1,0]
	s_nop 0
	v_pk_add_f32 v[4:5], v[4:5], v[8:9] op_sel:[1,0] op_sel_hi:[0,1]
	v_mov_b32_e32 v7, v4
	v_pk_add_f32 v[10:11], v[6:7], v[12:13] neg_lo:[0,1] neg_hi:[0,1]
	v_mov_b32_e32 v3, v8
	v_sub_f32_e32 v5, v6, v10
	v_pk_add_f32 v[2:3], v[2:3], v[10:11] neg_lo:[0,1] neg_hi:[0,1]
	v_sub_f32_e32 v5, v12, v5
	v_add_f32_e32 v2, v2, v5
	v_add_f32_e32 v2, v2, v3
	v_add_f32_e32 v2, v4, v2
	v_cndmask_b32_e32 v2, v203, v2, vcc
	v_cmp_lt_f32_e64 vcc, |v16|, s10
	v_rndne_f32_e32 v3, v1
	s_nop 0
	v_cndmask_b32_e32 v26, v2, v16, vcc
	v_fma_f32 v2, v0, s42, -v1
	v_fmac_f32_e32 v2, 0xb2a5705f, v0
	v_sub_f32_e32 v1, v1, v3
	v_add_f32_e32 v1, v1, v2
	v_exp_f32_e32 v1, v1
	v_cvt_i32_f32_e32 v2, v3
	v_cmp_nlt_f32_e32 vcc, s9, v0
	v_ldexp_f32 v1, v1, v2
	s_nop 0
	v_cndmask_b32_e32 v1, 0, v1, vcc
	v_cmp_ngt_f32_e32 vcc, s0, v0
	s_nop 1
	v_cndmask_b32_e32 v14, v203, v1, vcc
	v_add_f32_e32 v2, 1.0, v14
	v_add_f32_e32 v0, -1.0, v2
	v_sub_f32_e32 v1, v0, v2
	v_add_f32_e32 v1, 1.0, v1
	v_sub_f32_e32 v0, v14, v0
	v_add_f32_e32 v3, v0, v1
	v_frexp_mant_f32_e32 v0, v2
	v_cmp_gt_f32_e32 vcc, s11, v0
	v_cvt_f64_f32_e32 v[0:1], v2
	v_frexp_exp_i32_f64_e32 v0, v[0:1]
	v_subbrev_co_u32_e32 v8, vcc, 0, v0, vcc
	v_sub_u32_e32 v0, 0, v8
	v_ldexp_f32 v1, v2, v0
	v_add_f32_e32 v2, -1.0, v1
	v_add_f32_e32 v4, 1.0, v1
	v_ldexp_f32 v0, v3, v0
	v_add_f32_e32 v3, 1.0, v2
	v_add_f32_e32 v5, -1.0, v4
; __device__ __forceinline__ float log_sigmoid(float x) { return -log1pf(expf(-x)); }
; __device__ __forceinline__ void m3_outputs(const KQ p_in, int e, bool ctx_full, unsigned char* smem, unsigned* scan_word) {
;     ...
;             for (int q = 0; q < 2; ++q) { const int idx = tid + 512 * q; const int r = idx >> 3, pc = idx & 7; const bf16_t* zr = Z + (size_t)(t0 + r) * INW + h * 64 + pc * 8;
;                 *(u32x4*)(Kt + r * 72 + pc * 8) = *(const u32x4*)(zr + 1792);
;                 const bf16x8 vv = *(const bf16x8*)(zr + 2304);
; #pragma unroll
;                 for (int j = 0; j < 8; ++j) Vt[(pc * 8 + j) * 136 + (r ^ (pc << 2))] = (bf16_t)vv[j]; }
;             const size_t so = ((size_t)(b * NCH + cidx) * 8 + h) * 4096;
;             {
;                 const int ee = tid & 63, d0 = (tid >> 6) * 8;
;                 float tf[8], tb[8];
; #pragma unroll
;                 for (int j = 0; j < 8; ++j) { tf[j] = TF[so + (d0 + j) * 64 + ee]; tb[j] = TB[so + (d0 + j) * 64 + ee]; }
	v_sub_f32_e32 v3, v1, v3
	v_sub_f32_e32 v1, v1, v5
	v_add_f32_e32 v3, v0, v3
	v_add_f32_e32 v0, v0, v1
	v_add_f32_e32 v9, v4, v0
	v_rcp_f32_e32 v11, v9
	v_sub_f32_e32 v1, v4, v9
	v_add_f32_e32 v10, v0, v1
	v_add_f32_e32 v1, v2, v3
	v_mul_f32_e32 v13, v1, v11
	v_sub_f32_e32 v0, v2, v1
	v_mul_f32_e32 v2, v9, v13
	v_fma_f32 v4, v13, v9, -v2
	v_fmac_f32_e32 v4, v13, v10
	v_add_f32_e32 v12, v3, v0
	v_add_f32_e32 v0, v2, v4
	v_sub_f32_e32 v3, v1, v0
	v_pk_add_f32 v[6:7], v[0:1], v[2:3] neg_lo:[0,1] neg_hi:[0,1]
	v_mov_b32_e32 v5, v0
	v_pk_add_f32 v[0:1], v[6:7], v[4:5] neg_lo:[0,1] neg_hi:[0,1]
	v_cmp_neq_f32_e32 vcc, s1, v14
	v_add_f32_e32 v1, v12, v1
	v_add_f32_e32 v0, v0, v1
	v_add_f32_e32 v1, v3, v0
	v_mul_f32_e32 v12, v11, v1
	v_mul_f32_e32 v2, v9, v12
	v_fma_f32 v4, v12, v9, -v2
	v_fmac_f32_e32 v4, v12, v10
	v_sub_f32_e32 v3, v3, v1
	v_add_f32_e32 v9, v0, v3
	v_add_f32_e32 v0, v2, v4
	v_sub_f32_e32 v3, v1, v0
	v_pk_add_f32 v[6:7], v[0:1], v[2:3] neg_lo:[0,1] neg_hi:[0,1]
	v_mov_b32_e32 v5, v0
	v_pk_add_f32 v[0:1], v[6:7], v[4:5] neg_lo:[0,1] neg_hi:[0,1]
	s_nop 0
	v_add_f32_e32 v1, v9, v1
	v_add_f32_e32 v0, v0, v1
	v_add_f32_e32 v1, v13, v12
	v_add_f32_e32 v0, v3, v0
	v_sub_f32_e32 v2, v1, v13
	v_mul_f32_e32 v0, v11, v0
	v_sub_f32_e32 v2, v12, v2
	v_add_f32_e32 v2, v2, v0
	v_add_f32_e32 v4, v1, v2
	v_mul_f32_e32 v5, v4, v4
	v_fmamk_f32 v0, v5, 0x3e9b6dac, v191
	v_fmaak_f32 v149, v5, v0, 0x3f2aaada
	v_cvt_f32_i32_e32 v0, v8
	v_sub_f32_e32 v1, v4, v1
	v_sub_f32_e32 v1, v2, v1
	v_ldexp_f32 v6, v1, 1
	v_mul_f32_e32 v1, v4, v5
	v_ldexp_f32 v3, v4, 1
	v_pk_mul_f32 v[4:5], v[0:1], v[148:149]
	s_nop 0
	v_fma_f32 v2, v0, s12, -v4
	v_fmac_f32_e32 v2, 0xb102e308, v0
	v_pk_add_f32 v[0:1], v[4:5], v[2:3]
	s_nop 0
	v_sub_f32_e32 v3, v1, v3
	v_sub_f32_e32 v3, v5, v3
	v_add_f32_e32 v7, v6, v3
	v_mov_b32_e32 v6, v4
	v_pk_add_f32 v[4:5], v[0:1], v[4:5] neg_lo:[0,1] neg_hi:[0,1]
	v_pk_add_f32 v[8:9], v[0:1], v[6:7]
	v_mov_b32_e32 v3, v0
	v_mov_b32_e32 v5, v9
	v_pk_add_f32 v[10:11], v[2:3], v[4:5] neg_lo:[0,1] neg_hi:[0,1]
	v_pk_add_f32 v[2:3], v[2:3], v[4:5]
	v_mov_b32_e32 v6, v7
	v_pk_add_f32 v[4:5], v[2:3], v[0:1] op_sel:[1,0] op_sel_hi:[0,1] neg_lo:[0,1] neg_hi:[0,1]
	v_pk_add_f32 v[12:13], v[8:9], v[4:5] op_sel_hi:[1,0] neg_lo:[0,1] neg_hi:[0,1]
	v_mov_b32_e32 v8, v9
	v_mov_b32_e32 v9, v3
	v_pk_mov_b32 v[4:5], v[0:1], v[4:5] op_sel:[1,0]
	v_mov_b32_e32 v7, v0
	v_pk_add_f32 v[4:5], v[8:9], v[4:5] neg_lo:[0,1] neg_hi:[0,1]
	v_mov_b32_e32 v12, v10
	v_pk_add_f32 v[0:1], v[6:7], v[4:5] neg_lo:[0,1] neg_hi:[0,1]
	v_mov_b32_e32 v11, v3
	v_pk_add_f32 v[4:5], v[12:13], v[0:1]
	s_nop 0
	v_pk_add_f32 v[6:7], v[4:5], v[4:5] op_sel:[0,1] op_sel_hi:[1,0]
	s_nop 0
	v_pk_add_f32 v[2:3], v[2:3], v[6:7] op_sel:[1,0] op_sel_hi:[0,1]
	v_mov_b32_e32 v5, v2
	v_pk_add_f32 v[8:9], v[4:5], v[10:11] neg_lo:[0,1] neg_hi:[0,1]
	v_mov_b32_e32 v1, v6
	v_sub_f32_e32 v3, v4, v8
	v_pk_add_f32 v[0:1], v[0:1], v[8:9] neg_lo:[0,1] neg_hi:[0,1]
	v_sub_f32_e32 v3, v10, v3
	v_add_f32_e32 v0, v0, v3
	v_add_f32_e32 v0, v0, v1
	v_add_f32_e32 v0, v2, v0
	v_cndmask_b32_e32 v0, v203, v0, vcc
	v_cmp_lt_f32_e64 vcc, |v14|, s10
	v_add_u32_e32 v2, s7, v114
	s_nop 0
	v_cndmask_b32_e32 v27, v0, v14, vcc
	v_lshl_add_u64 v[0:1], v[82:83], 0, s[80:81]
	v_mad_i64_i32 v[6:7], s[0:1], v2, s54, v[0:1]
	global_load_dwordx4 v[64:67], v[6:7], off offset:3584
	v_add_co_u32_e32 v2, vcc, s43, v6
	s_nop 1
	v_addc_co_u32_e32 v3, vcc, 0, v7, vcc
	global_load_dwordx4 v[68:71], v[2:3], off offset:512
	v_add_u32_e32 v2, s7, v115
	v_mad_i64_i32 v[4:5], s[0:1], v2, s54, v[0:1]
	global_load_dwordx4 v[72:75], v[4:5], off offset:3584
	v_add_co_u32_e32 v0, vcc, s43, v4
	s_nop 1
	v_addc_co_u32_e32 v1, vcc, 0, v5, vcc
	global_load_dwordx4 v[76:79], v[0:1], off offset:512
	s_mul_i32 s0, s5, 34
	s_add_i32 s0, s0, s8
	s_ashr_i32 s1, s0, 31
	s_lshl_b64 s[0:1], s[0:1], 15
	s_lshl_b32 s7, s6, 12
	s_or_b32 s0, s0, s7
	v_mov_b32_e32 v3, s1
	v_or_b32_e32 v2, s0, v80
	v_lshl_add_u64 v[0:1], v[2:3], 0, v[90:91]
	v_lshl_add_u64 v[6:7], v[2:3], 0, v[92:93]
	v_lshl_add_u64 v[10:11], v[2:3], 0, v[94:95]
	v_lshl_add_u64 v[14:15], v[2:3], 0, v[96:97]
	v_lshl_add_u64 v[18:19], v[2:3], 0, v[98:99]
	v_lshlrev_b64 v[0:1], 2, v[0:1]
	v_lshlrev_b64 v[6:7], 2, v[6:7]
	v_lshlrev_b64 v[10:11], 2, v[10:11]
	v_lshlrev_b64 v[14:15], 2, v[14:15]
	v_lshlrev_b64 v[18:19], 2, v[18:19]
	v_lshl_add_u64 v[22:23], v[2:3], 0, v[100:101]
	v_lshl_add_u64 v[28:29], v[2:3], 0, v[102:103]
	v_lshl_add_u64 v[2:3], v[2:3], 0, v[104:105]
	v_lshl_add_u64 v[4:5], s[92:93], 0, v[0:1]
	v_lshl_add_u64 v[8:9], s[92:93], 0, v[6:7]
	v_lshl_add_u64 v[6:7], s[94:95], 0, v[6:7]
	v_lshl_add_u64 v[12:13], s[92:93], 0, v[10:11]
	v_lshl_add_u64 v[10:11], s[94:95], 0, v[10:11]
	v_lshl_add_u64 v[16:17], s[92:93], 0, v[14:15]
	v_lshl_add_u64 v[14:15], s[94:95], 0, v[14:15]
	v_lshl_add_u64 v[20:21], s[92:93], 0, v[18:19]
	v_lshl_add_u64 v[18:19], s[94:95], 0, v[18:19]
	v_lshlrev_b64 v[22:23], 2, v[22:23]
	v_lshlrev_b64 v[28:29], 2, v[28:29]
	v_lshlrev_b64 v[2:3], 2, v[2:3]
	v_lshl_add_u64 v[0:1], s[94:95], 0, v[0:1]
	v_lshl_add_u64 v[24:25], s[92:93], 0, v[22:23]
	v_lshl_add_u64 v[22:23], s[94:95], 0, v[22:23]
	v_lshl_add_u64 v[30:31], s[92:93], 0, v[28:29]
	v_lshl_add_u64 v[28:29], s[94:95], 0, v[28:29]
	v_lshl_add_u64 v[32:33], s[92:93], 0, v[2:3]
	v_lshl_add_u64 v[2:3], s[94:95], 0, v[2:3]
	global_load_dword v8, v[8:9], off
	s_nop 0
	global_load_dword v4, v[4:5], off
	s_nop 0
	global_load_dword v5, v[16:17], off
	global_load_dword v9, v[12:13], off
	s_nop 0
	global_load_dword v12, v[24:25], off
	global_load_dword v13, v[20:21], off
	global_load_dword v16, v[32:33], off
	global_load_dword v17, v[30:31], off
	s_nop 0
	global_load_dword v6, v[6:7], off
	s_nop 0
	global_load_dword v7, v[0:1], off
	s_nop 0
	global_load_dword v14, v[14:15], off
	s_nop 0
	global_load_dword v10, v[10:11], off
	s_nop 0
	global_load_dword v11, v[22:23], off
	global_load_dword v15, v[18:19], off
	s_nop 0
	global_load_dword v18, v[2:3], off
	global_load_dword v19, v[28:29], off
	s_waitcnt lgkmcnt(0)
; __device__ __forceinline__ void m3_outputs(const KQ p_in, int e, bool ctx_full, unsigned char* smem, unsigned* scan_word) {
;     ...
;             for (int q = 0; q < 2; ++q) { const int idx = tid + 512 * q; const int r = idx >> 3, pc = idx & 7; const bf16_t* zr = Z + (size_t)(t0 + r) * INW + h * 64 + pc * 8;
;                 *(u32x4*)(Kt + r * 72 + pc * 8) = *(const u32x4*)(zr + 1792);
;                 const bf16x8 vv = *(const bf16x8*)(zr + 2304);
; #pragma unroll
;                 for (int j = 0; j < 8; ++j) Vt[(pc * 8 + j) * 136 + (r ^ (pc << 2))] = (bf16_t)vv[j]; }
;             const size_t so = ((size_t)(b * NCH + cidx) * 8 + h) * 4096;
;             {
;                 const int ee = tid & 63, d0 = (tid >> 6) * 8;
;                 float tf[8], tb[8];
; #pragma unroll
;                 for (int j = 0; j < 8; ++j) { tf[j] = TF[so + (d0 + j) * 64 + ee]; tb[j] = TB[so + (d0 + j) * 64 + ee]; }
;                 u32x4 wf4, wb4;
;                 wf4.x = pg8::cvt_pk_bf16(tf[0], tf[1]); wf4.y = pg8::cvt_pk_bf16(tf[2], tf[3]); wf4.z = pg8::cvt_pk_bf16(tf[4], tf[5]); wf4.w = pg8::cvt_pk_bf16(tf[6], tf[7]);
;                 wb4.x = pg8::cvt_pk_bf16(tb[0], tb[1]); wb4.y = pg8::cvt_pk_bf16(tb[2], tb[3]); wb4.z = pg8::cvt_pk_bf16(tb[4], tb[5]); wb4.w = pg8::cvt_pk_bf16(tb[6], tb[7]);
;                 *(u32x4*)(TfT + ee * 72 + d0) = wf4; *(u32x4*)(TbT + ee * 72 + d0) = wb4;
;             }
;             __builtin_amdgcn_sched_barrier(0);
;             bf16x8 qf[2], qff[2], qfb[2];
;             { const bf16_t* qr = Z + (size_t)(t0 + i) * INW + 512 + h * 64 + 8 * g4;
;               const float cf = __expf(lgf * (float)(i + 1)), cb = __expf(lgb * (float)(128 - i));
; #pragma unroll
;               for (int k2 = 0; k2 < 2; ++k2) { qf[k2] = *(const bf16x8*)(qr + 32 * k2);
;                   f32x4 a0, a1, b0, b1;
; #pragma unroll
;                   for (int j = 0; j < 4; ++j) { const float x0 = bf2f((bf16_t)qf[k2][j]), x1 = bf2f((bf16_t)qf[k2][4 + j]); a0[j] = x0 * cf; a1[j] = x1 * cf; b0[j] = x0 * cb; b1[j] = x1 * cb; }
;                   qff[k2] = pack8(a0, a1); qfb[k2] = pack8(b0, b1); } }
;             __builtin_amdgcn_sched_barrier(0);
;             __syncthreads();
; #pragma unroll
;             for (int m = 0; m < 4; ++m)
; #pragma unroll
;                 for (int k2 = 0; k2 < 2; ++k2) {
	s_waitcnt vmcnt(19) lgkmcnt(0)
	ds_write_b128 v158, v[64:67]
	s_waitcnt vmcnt(18)
	ds_write_b16 v159, v68 offset:18432
	ds_write_b16_d16_hi v159, v68 offset:18704
	ds_write_b16 v159, v69 offset:18976
	ds_write_b16_d16_hi v159, v69 offset:19248
	ds_write_b16 v159, v70 offset:19520
	ds_write_b16_d16_hi v159, v70 offset:19792
	ds_write_b16 v159, v71 offset:20064
	ds_write_b16_d16_hi v159, v71 offset:20336
	s_waitcnt vmcnt(17)
	ds_write_b128 v160, v[72:75]
	s_waitcnt vmcnt(16)
	ds_write_b16 v161, v76 offset:18432
	ds_write_b16_d16_hi v161, v76 offset:18704
	ds_write_b16 v161, v77 offset:18976
	ds_write_b16_d16_hi v161, v77 offset:19248
	ds_write_b16 v161, v78 offset:19520
	ds_write_b16_d16_hi v161, v78 offset:19792
	ds_write_b16 v161, v79 offset:20064
	ds_write_b16_d16_hi v161, v79 offset:20336
	s_waitcnt vmcnt(14)
	v_cvt_pk_bf16_f32 v0, v4, v8
	s_waitcnt vmcnt(12)
	v_cvt_pk_bf16_f32 v1, v9, v5
	s_waitcnt vmcnt(10)
	v_cvt_pk_bf16_f32 v2, v13, v12
	s_waitcnt vmcnt(8)
	v_cvt_pk_bf16_f32 v3, v17, v16
	s_waitcnt vmcnt(6)
	v_cvt_pk_bf16_f32 v4, v7, v6
	s_waitcnt vmcnt(4)
	v_cvt_pk_bf16_f32 v5, v10, v14
	s_waitcnt vmcnt(2)
	v_cvt_pk_bf16_f32 v6, v15, v11
	s_waitcnt vmcnt(0)
	v_cvt_pk_bf16_f32 v7, v19, v18
	ds_write_b128 v85, v[0:3] offset:35840
	ds_write_b128 v85, v[4:7] offset:45056
	v_mov_b64_e32 v[0:1], s[88:89]
	v_mad_i64_i32 v[0:1], s[0:1], v106, s54, v[0:1]
	v_lshl_add_u64 v[24:25], v[0:1], 0, s[80:81]
	v_lshl_add_u64 v[4:5], v[24:25], 0, v[144:145]
	global_load_dwordx4 v[0:3], v[4:5], off offset:1024
	global_load_dwordx4 v[64:67], v[4:5], off offset:1088
	v_mul_f32_e32 v6, v87, v26
	v_mul_f32_e32 v7, v110, v27
	v_mul_f32_e32 v6, 0xbfb8aa3b, v6
	v_mul_f32_e32 v7, 0xbfb8aa3b, v7
	v_exp_f32_e32 v6, v6
	v_exp_f32_e32 v7, v7
	s_waitcnt lgkmcnt(0)
	s_waitcnt vmcnt(1)
	v_lshlrev_b32_e32 v8, 16, v0
	v_lshlrev_b32_e32 v9, 16, v2
	v_and_b32_e32 v10, 0xffff0000, v0
	v_and_b32_e32 v11, 0xffff0000, v2
	v_lshlrev_b32_e32 v12, 16, v1
	v_lshlrev_b32_e32 v13, 16, v3
	v_and_b32_e32 v14, 0xffff0000, v1
	v_and_b32_e32 v15, 0xffff0000, v3
	v_mul_f32_e32 v16, v6, v8
	v_mul_f32_e32 v18, v6, v9
	v_mul_f32_e32 v17, v6, v10
	v_mul_f32_e32 v19, v6, v11
	v_mul_f32_e32 v20, v6, v12
	v_mul_f32_e32 v21, v6, v13
	v_mul_f32_e32 v22, v6, v14
	v_mul_f32_e32 v23, v6, v15
	v_mul_f32_e32 v8, v7, v8
	v_mul_f32_e32 v9, v7, v9
	v_mul_f32_e32 v10, v7, v10
	v_mul_f32_e32 v11, v7, v11
	v_mul_f32_e32 v12, v7, v12
	v_mul_f32_e32 v13, v7, v13
	v_mul_f32_e32 v14, v7, v14
	v_mul_f32_e32 v15, v7, v15
	v_cvt_pk_bf16_f32 v16, v16, v17
	v_cvt_pk_bf16_f32 v17, v20, v22
	v_cvt_pk_bf16_f32 v18, v18, v19
	v_cvt_pk_bf16_f32 v19, v21, v23
	v_cvt_pk_bf16_f32 v28, v8, v10
	v_cvt_pk_bf16_f32 v29, v12, v14
	v_cvt_pk_bf16_f32 v30, v9, v11
	v_cvt_pk_bf16_f32 v31, v13, v15
	s_waitcnt vmcnt(0)
	v_mov_b32_e32 v20, v64
	v_mov_b32_e32 v21, v65
	v_mov_b32_e32 v22, v66
	v_mov_b32_e32 v23, v67
	s_waitcnt lgkmcnt(0)
	s_waitcnt vmcnt(0)
	v_and_b32_e32 v8, 0xffff0000, v64
	v_and_b32_e32 v9, 0xffff0000, v66
	v_lshlrev_b32_e32 v10, 16, v65
	v_lshlrev_b32_e32 v11, 16, v67
	v_and_b32_e32 v12, 0xffff0000, v65
	v_lshlrev_b32_e32 v4, 16, v64
	v_lshlrev_b32_e32 v5, 16, v66
	v_and_b32_e32 v13, 0xffff0000, v67
	v_mul_f32_e32 v32, v6, v8
	v_mul_f32_e32 v34, v6, v9
	v_mul_f32_e32 v33, v6, v10
	v_mul_f32_e32 v35, v6, v11
	v_mul_f32_e32 v36, v6, v12
	v_mul_f32_e32 v14, v6, v4
	v_mul_f32_e32 v15, v6, v5
	v_mul_f32_e32 v4, v7, v4
	v_mul_f32_e32 v5, v7, v5
	v_mul_f32_e32 v8, v7, v8
	v_mul_f32_e32 v9, v7, v9
	v_mul_f32_e32 v10, v7, v10
	v_mul_f32_e32 v11, v7, v11
	v_mul_f32_e32 v6, v6, v13
	v_mul_f32_e32 v12, v7, v12
	v_mul_f32_e32 v7, v7, v13
	v_cvt_pk_bf16_f32 v32, v14, v32
	v_cvt_pk_bf16_f32 v33, v33, v36
	v_cvt_pk_bf16_f32 v34, v15, v34
	v_cvt_pk_bf16_f32 v35, v35, v6
	v_cvt_pk_bf16_f32 v36, v4, v8
	v_cvt_pk_bf16_f32 v37, v10, v12
	v_cvt_pk_bf16_f32 v38, v5, v9
	v_cvt_pk_bf16_f32 v39, v11, v7
	s_barrier
	ds_read_b128 v[208:211], v116 offset:35840
	ds_read_b128 v[212:215], v116 offset:45056
	ds_read_b128 v[216:219], v116 offset:35904
	ds_read_b128 v[220:223], v116 offset:45120
	ds_read_b128 v[224:227], v116 offset:38144
	ds_read_b128 v[228:231], v116 offset:47360
	ds_read_b128 v[232:235], v116 offset:38208
	ds_read_b128 v[236:239], v116 offset:47424
	s_waitcnt lgkmcnt(7)
	v_mfma_f32_16x16x32_bf16 v[4:7], v[208:211], v[16:19], 0
	s_waitcnt lgkmcnt(6)
	v_mfma_f32_16x16x32_bf16 v[4:7], v[212:215], v[28:31], v[4:7]
	s_waitcnt lgkmcnt(5)
	v_mfma_f32_16x16x32_bf16 v[4:7], v[216:219], v[32:35], v[4:7]
	s_waitcnt lgkmcnt(4)
	v_mfma_f32_16x16x32_bf16 v[4:7], v[220:223], v[36:39], v[4:7]
	s_waitcnt lgkmcnt(3)
	v_mfma_f32_16x16x32_bf16 v[8:11], v[224:227], v[16:19], 0
	s_waitcnt lgkmcnt(2)
	v_mfma_f32_16x16x32_bf16 v[8:11], v[228:231], v[28:31], v[8:11]
	s_waitcnt lgkmcnt(1)
	v_mfma_f32_16x16x32_bf16 v[8:11], v[232:235], v[32:35], v[8:11]
	s_waitcnt lgkmcnt(0)
	v_mfma_f32_16x16x32_bf16 v[8:11], v[236:239], v[36:39], v[8:11]
	ds_read_b128 v[208:211], v116 offset:40448
	ds_read_b128 v[212:215], v116 offset:49664
	ds_read_b128 v[216:219], v116 offset:40512
	ds_read_b128 v[220:223], v116 offset:49728
	ds_read_b128 v[224:227], v116 offset:42752
	ds_read_b128 v[228:231], v116 offset:51968
	ds_read_b128 v[232:235], v116 offset:42816
	ds_read_b128 v[236:239], v116 offset:52032
	s_waitcnt lgkmcnt(7)
	v_mfma_f32_16x16x32_bf16 v[12:15], v[208:211], v[16:19], 0
	s_waitcnt lgkmcnt(6)
	v_mfma_f32_16x16x32_bf16 v[12:15], v[212:215], v[28:31], v[12:15]
	s_waitcnt lgkmcnt(5)
	v_mfma_f32_16x16x32_bf16 v[12:15], v[216:219], v[32:35], v[12:15]
	s_waitcnt lgkmcnt(4)
	v_mfma_f32_16x16x32_bf16 v[12:15], v[220:223], v[36:39], v[12:15]
	s_waitcnt lgkmcnt(3)
; __device__ __forceinline__ void m3_outputs(const KQ p_in, int e, bool ctx_full, unsigned char* smem, unsigned* scan_word) {
;     ...
;             for (int m = 0; m < 4; ++m)
; #pragma unroll
;                 for (int k2 = 0; k2 < 2; ++k2) {
;                     const bf16x8 af = *(const bf16x8*)(TfT + (16 * m + ln) * 72 + 32 * k2 + 8 * g4);
;                     const bf16x8 ab = *(const bf16x8*)(TbT + (16 * m + ln) * 72 + 32 * k2 + 8 * g4);
;                     O[m] = __builtin_amdgcn_mfma_f32_16x16x32_bf16(af, qff[k2], O[m], 0, 0, 0);
;                     O[m] = __builtin_amdgcn_mfma_f32_16x16x32_bf16(ab, qfb[k2], O[m], 0, 0, 0);
;                     __builtin_amdgcn_sched_barrier(0);
;                 }
;             const float lf2 = lgf * 1.44269504f, lb2 = lgb * 1.44269504f; const int di = i - 4 * g4;
;             const float bfw = lf2 * (float)di, bbw = -lb2 * (float)di;
;             f32x4 st[8];
; #pragma unroll
;             for (int mt = 0; mt < 8; ++mt) {
;                 f32x4 a = (f32x4){0.f, 0.f, 0.f, 0.f};
; #pragma unroll
;                 for (int k2 = 0; k2 < 2; ++k2) { const bf16x8 kf = *(const bf16x8*)(Kt + (16 * mt + ln) * 72 + 32 * k2 + 8 * g4); a = __builtin_amdgcn_mfma_f32_16x16x32_bf16(kf, qf[k2], a, 0, 0, 0); }
; #pragma unroll
;                 for (int rg = 0; rg < 4; ++rg) { const int cc = 16 * mt + rg; const int df = di - cc;
;                     const float arg = (df > 0) ? fmaf(-lf2, (float)cc, bfw) : fmaf(lb2, (float)cc, bbw);
;                     float wgt = __builtin_amdgcn_exp2f(arg); wgt = (df == 0) ? 2.0f : wgt;
;                     a[rg] *= wgt; }
;                 st[mt] = a;
;                 __builtin_amdgcn_sched_barrier(0);
	v_mfma_f32_16x16x32_bf16 v[16:19], v[224:227], v[16:19], 0
	s_waitcnt lgkmcnt(2)
	v_mfma_f32_16x16x32_bf16 v[16:19], v[228:231], v[28:31], v[16:19]
	s_waitcnt lgkmcnt(1)
	v_mfma_f32_16x16x32_bf16 v[16:19], v[232:235], v[32:35], v[16:19]
	s_waitcnt lgkmcnt(0)
	v_mfma_f32_16x16x32_bf16 v[16:19], v[236:239], v[36:39], v[16:19]
	v_add_u32_e32 v33, v111, v117
	ds_read_b128 v[208:211], v33
	ds_read_b128 v[212:215], v33 offset:64
	ds_read_b128 v[216:219], v33 offset:2304
	ds_read_b128 v[220:223], v33 offset:2368
	s_nop 0
	v_mul_f32_e32 v28, 0xbfb8aa3b, v26
	v_mul_f32_e32 v26, 0xbfb8aa3b, v27
	v_mul_f32_e32 v27, v28, v112
	v_mul_f32_e64 v29, v112, -v26
	v_readlane_b32 s0, v253, 41
	v_fmamk_f32 v30, v28, 0x80000000, v27
	v_fma_f32 v31, 0, v26, v29
	v_readlane_b32 s1, v253, 42
	s_waitcnt lgkmcnt(3)
	v_mfma_f32_16x16x32_bf16 v[34:37], v[208:211], v[0:3], 0
	v_fma_f32 v32, v112, -v26, v26
	v_cndmask_b32_e64 v30, v31, v30, s[0:1]
	v_exp_f32_e32 v30, v30
	v_readlane_b32 s0, v253, 43
	v_readlane_b32 s1, v253, 44
	v_fma_f32 v31, v28, v112, -v28
	s_waitcnt lgkmcnt(2)
	v_mfma_f32_16x16x32_bf16 v[34:37], v[212:215], v[20:23], v[34:37]
	v_cndmask_b32_e64 v30, v30, 2.0, s[0:1]
	v_readlane_b32 s0, v253, 45
	v_readlane_b32 s1, v253, 46
	s_nop 1
	v_cndmask_b32_e64 v31, v32, v31, s[0:1]
	v_exp_f32_e32 v31, v31
	v_readlane_b32 s0, v253, 47
	v_readlane_b32 s1, v253, 48
	v_mul_f32_e32 v30, v30, v34
	v_fma_f32 v32, -2.0, v28, v27
	v_cndmask_b32_e64 v31, v31, 2.0, s[0:1]
	v_readlane_b32 s0, v253, 49
	v_fma_f32 v34, 2.0, v26, v29
	v_readlane_b32 s1, v253, 50
	v_mul_f32_e32 v31, v31, v35
	v_fmamk_f32 v35, v26, 0x40400000, v29
	v_cndmask_b32_e64 v32, v34, v32, s[0:1]
	v_exp_f32_e32 v32, v32
	v_readlane_b32 s0, v253, 51
	v_readlane_b32 s1, v253, 52
	v_fmamk_f32 v34, v28, 0xc0400000, v27
	s_nop 0
	v_cndmask_b32_e64 v32, v32, 2.0, s[0:1]
	v_readlane_b32 s0, v253, 53
	v_readlane_b32 s1, v253, 54
	v_mul_f32_e32 v32, v32, v36
	s_nop 0
	v_cndmask_b32_e64 v34, v35, v34, s[0:1]
	v_exp_f32_e32 v34, v34
	v_readlane_b32 s0, v253, 55
	v_readlane_b32 s1, v253, 56
	s_nop 1
	v_cndmask_b32_e64 v34, v34, 2.0, s[0:1]
	v_mul_f32_e32 v34, v34, v37
	ds_read_b128 v[208:211], v33 offset:4608
	ds_read_b128 v[212:215], v33 offset:4672
	s_nop 0
	v_readlane_b32 s0, v253, 57
	v_fmamk_f32 v35, v28, 0xc1800000, v27
	v_readlane_b32 s1, v253, 58
	s_waitcnt lgkmcnt(3)
	v_mfma_f32_16x16x32_bf16 v[36:39], v[216:219], v[0:3], 0
	s_waitcnt lgkmcnt(2)
	v_mfma_f32_16x16x32_bf16 v[36:39], v[220:223], v[20:23], v[36:39]
	v_fmamk_f32 v40, v26, 0x41800000, v29
	v_cndmask_b32_e64 v35, v40, v35, s[0:1]
	v_exp_f32_e32 v35, v35
	v_readlane_b32 s0, v253, 59
	v_readlane_b32 s1, v253, 60
	v_fmamk_f32 v40, v26, 0x41880000, v29
	s_nop 0
	v_cndmask_b32_e64 v35, v35, 2.0, s[0:1]
	v_readlane_b32 s0, v253, 61
	v_mul_f32_e32 v35, v35, v36
	v_fmamk_f32 v36, v28, 0xc1880000, v27
	v_readlane_b32 s1, v253, 62
	s_nop 1
	v_cndmask_b32_e64 v36, v40, v36, s[0:1]
	v_exp_f32_e32 v36, v36
	v_readlane_b32 s0, v253, 63
	v_readlane_b32 s1, v254, 0
	v_fmamk_f32 v40, v26, 0x41900000, v29
	s_nop 0
	v_cndmask_b32_e64 v36, v36, 2.0, s[0:1]
	v_readlane_b32 s0, v254, 1
	v_mul_f32_e32 v36, v36, v37
	v_fmamk_f32 v37, v28, 0xc1900000, v27
	v_readlane_b32 s1, v254, 2
	s_nop 1
	v_cndmask_b32_e64 v37, v40, v37, s[0:1]
	v_exp_f32_e32 v37, v37
	v_readlane_b32 s0, v254, 3
	v_readlane_b32 s1, v254, 4
	v_fmamk_f32 v40, v26, 0x41980000, v29
	s_nop 0
	v_cndmask_b32_e64 v37, v37, 2.0, s[0:1]
	v_readlane_b32 s0, v254, 5
	v_mul_f32_e32 v38, v37, v38
	v_fmamk_f32 v37, v28, 0xc1980000, v27
	v_readlane_b32 s1, v254, 6
	s_nop 1
	v_cndmask_b32_e64 v37, v40, v37, s[0:1]
	v_exp_f32_e32 v37, v37
	v_readlane_b32 s0, v254, 7
	v_readlane_b32 s1, v254, 8
	s_nop 1
	v_cndmask_b32_e64 v37, v37, 2.0, s[0:1]
	v_mul_f32_e32 v40, v37, v39
	ds_read_b128 v[216:219], v33 offset:6912
	ds_read_b128 v[220:223], v33 offset:6976
	s_nop 0
	v_readlane_b32 s0, v254, 9
	v_fmamk_f32 v37, v28, 0xc2000000, v27
	v_fmamk_f32 v39, v26, 0x42000000, v29
	v_readlane_b32 s1, v254, 10
	v_fmamk_f32 v41, v26, 0x42040000, v29
	s_waitcnt lgkmcnt(3)
	v_mfma_f32_16x16x32_bf16 v[42:45], v[208:211], v[0:3], 0
	v_cndmask_b32_e64 v37, v39, v37, s[0:1]
	v_exp_f32_e32 v37, v37
	v_readlane_b32 s0, v254, 11
	v_readlane_b32 s1, v254, 12
	v_fmamk_f32 v39, v28, 0xc2040000, v27
	s_waitcnt lgkmcnt(2)
	v_mfma_f32_16x16x32_bf16 v[42:45], v[212:215], v[20:23], v[42:45]
	v_cndmask_b32_e64 v37, v37, 2.0, s[0:1]
	v_readlane_b32 s0, v254, 13
	v_readlane_b32 s1, v254, 14
	s_nop 1
	v_cndmask_b32_e64 v39, v41, v39, s[0:1]
	v_exp_f32_e32 v39, v39
	v_readlane_b32 s0, v254, 15
	v_readlane_b32 s1, v254, 16
	v_mul_f32_e32 v37, v37, v42
	v_fmamk_f32 v41, v28, 0xc2080000, v27
	v_cndmask_b32_e64 v39, v39, 2.0, s[0:1]
	v_readlane_b32 s0, v254, 17
	v_fmamk_f32 v42, v26, 0x42080000, v29
	v_readlane_b32 s1, v254, 18
	v_mul_f32_e32 v39, v39, v43
	v_fmamk_f32 v43, v26, 0x420c0000, v29
	v_cndmask_b32_e64 v41, v42, v41, s[0:1]
	v_exp_f32_e32 v41, v41
	v_readlane_b32 s0, v254, 19
	v_readlane_b32 s1, v254, 20
	v_fmamk_f32 v42, v28, 0xc20c0000, v27
	s_nop 0
	v_cndmask_b32_e64 v41, v41, 2.0, s[0:1]
	v_readlane_b32 s0, v254, 21
	v_readlane_b32 s1, v254, 22
	v_mul_f32_e32 v41, v41, v44
	s_nop 0
	v_cndmask_b32_e64 v42, v43, v42, s[0:1]
	v_exp_f32_e32 v42, v42
	v_readlane_b32 s0, v254, 23
	v_readlane_b32 s1, v254, 24
	s_nop 1
	v_cndmask_b32_e64 v42, v42, 2.0, s[0:1]
	v_mul_f32_e32 v42, v42, v45
	ds_read_b128 v[208:211], v33 offset:9216
	ds_read_b128 v[212:215], v33 offset:9280
	s_nop 0
	v_readlane_b32 s0, v254, 25
	v_fmamk_f32 v43, v28, 0xc2400000, v27
	v_readlane_b32 s1, v254, 26
	s_waitcnt lgkmcnt(3)
	v_mfma_f32_16x16x32_bf16 v[44:47], v[216:219], v[0:3], 0
	s_waitcnt lgkmcnt(2)
; __device__ __forceinline__ void m3_outputs(const KQ p_in, int e, bool ctx_full, unsigned char* smem, unsigned* scan_word) {
;     ...
;             for (int mt = 0; mt < 8; ++mt) {
;                 f32x4 a = (f32x4){0.f, 0.f, 0.f, 0.f};
; #pragma unroll
;                 for (int k2 = 0; k2 < 2; ++k2) { const bf16x8 kf = *(const bf16x8*)(Kt + (16 * mt + ln) * 72 + 32 * k2 + 8 * g4); a = __builtin_amdgcn_mfma_f32_16x16x32_bf16(kf, qf[k2], a, 0, 0, 0); }
; #pragma unroll
;                 for (int rg = 0; rg < 4; ++rg) { const int cc = 16 * mt + rg; const int df = di - cc;
;                     const float arg = (df > 0) ? fmaf(-lf2, (float)cc, bfw) : fmaf(lb2, (float)cc, bbw);
;                     float wgt = __builtin_amdgcn_exp2f(arg); wgt = (df == 0) ? 2.0f : wgt;
;                     a[rg] *= wgt; }
;                 st[mt] = a;
;                 __builtin_amdgcn_sched_barrier(0);
	v_mfma_f32_16x16x32_bf16 v[44:47], v[220:223], v[20:23], v[44:47]
	v_fmamk_f32 v48, v26, 0x42400000, v29
	v_cndmask_b32_e64 v43, v48, v43, s[0:1]
	v_exp_f32_e32 v43, v43
	v_readlane_b32 s0, v254, 27
	v_readlane_b32 s1, v254, 28
	v_fmamk_f32 v48, v26, 0x42440000, v29
	s_nop 0
	v_cndmask_b32_e64 v43, v43, 2.0, s[0:1]
	v_readlane_b32 s0, v254, 29
	v_mul_f32_e32 v43, v43, v44
	v_fmamk_f32 v44, v28, 0xc2440000, v27
	v_readlane_b32 s1, v254, 30
	s_nop 1
	v_cndmask_b32_e64 v44, v48, v44, s[0:1]
	v_exp_f32_e32 v44, v44
	v_readlane_b32 s0, v254, 31
	v_readlane_b32 s1, v254, 32
	v_fmamk_f32 v48, v26, 0x42480000, v29
	s_nop 0
	v_cndmask_b32_e64 v44, v44, 2.0, s[0:1]
	v_readlane_b32 s0, v254, 33
	v_mul_f32_e32 v44, v44, v45
	v_fmamk_f32 v45, v28, 0xc2480000, v27
	v_readlane_b32 s1, v254, 34
	s_nop 1
	v_cndmask_b32_e64 v45, v48, v45, s[0:1]
	v_exp_f32_e32 v45, v45
	v_readlane_b32 s0, v254, 35
	v_readlane_b32 s1, v254, 36
	v_fmamk_f32 v48, v26, 0x424c0000, v29
	s_nop 0
	v_cndmask_b32_e64 v45, v45, 2.0, s[0:1]
	v_readlane_b32 s0, v254, 37
	v_mul_f32_e32 v45, v45, v46
	v_fmamk_f32 v46, v28, 0xc24c0000, v27
	v_readlane_b32 s1, v254, 38
	s_nop 1
	v_cndmask_b32_e64 v46, v48, v46, s[0:1]
	v_exp_f32_e32 v46, v46
	v_readlane_b32 s0, v254, 39
	v_readlane_b32 s1, v254, 40
	s_nop 1
	v_cndmask_b32_e64 v46, v46, 2.0, s[0:1]
	v_mul_f32_e32 v54, v46, v47
	ds_read_b128 v[216:219], v33 offset:11520
	ds_read_b128 v[220:223], v33 offset:11584
	s_nop 0
	v_readlane_b32 s0, v254, 41
	v_readlane_b32 s1, v254, 42
	s_waitcnt lgkmcnt(3)
	v_mfma_f32_16x16x32_bf16 v[46:49], v[208:211], v[0:3], 0
	s_waitcnt lgkmcnt(2)
	v_mfma_f32_16x16x32_bf16 v[46:49], v[212:215], v[20:23], v[46:49]
	v_fmamk_f32 v50, v28, 0xc2800000, v27
	v_fmamk_f32 v51, v26, 0x42800000, v29
	v_cndmask_b32_e64 v50, v51, v50, s[0:1]
	v_exp_f32_e32 v50, v50
	v_readlane_b32 s0, v254, 43
	v_readlane_b32 s1, v254, 44
	s_nop 1
	v_cndmask_b32_e64 v50, v50, 2.0, s[0:1]
	v_readlane_b32 s0, v254, 45
	v_mul_f32_e32 v55, v50, v46
	v_fmamk_f32 v46, v28, 0xc2820000, v27
	v_fmamk_f32 v50, v26, 0x42820000, v29
	v_readlane_b32 s1, v254, 46
	s_nop 1
	v_cndmask_b32_e64 v46, v50, v46, s[0:1]
	v_exp_f32_e32 v46, v46
	v_readlane_b32 s0, v254, 47
	v_readlane_b32 s1, v254, 48
	s_nop 1
	v_cndmask_b32_e64 v46, v46, 2.0, s[0:1]
	v_readlane_b32 s0, v254, 49
	v_mul_f32_e32 v56, v46, v47
	v_fmamk_f32 v46, v28, 0xc2840000, v27
	v_fmamk_f32 v47, v26, 0x42840000, v29
	v_readlane_b32 s1, v254, 50
	s_nop 1
	v_cndmask_b32_e64 v46, v47, v46, s[0:1]
	v_exp_f32_e32 v46, v46
	v_readlane_b32 s0, v254, 51
	v_readlane_b32 s1, v254, 52
	v_fmamk_f32 v47, v26, 0x42860000, v29
	s_nop 0
	v_cndmask_b32_e64 v46, v46, 2.0, s[0:1]
	v_readlane_b32 s0, v254, 53
	v_mul_f32_e32 v57, v46, v48
	v_fmamk_f32 v46, v28, 0xc2860000, v27
	v_readlane_b32 s1, v254, 54
	s_nop 1
	v_cndmask_b32_e64 v46, v47, v46, s[0:1]
	v_exp_f32_e32 v46, v46
	v_readlane_b32 s0, v254, 55
	v_readlane_b32 s1, v254, 56
	s_nop 1
	v_cndmask_b32_e64 v46, v46, 2.0, s[0:1]
	v_mul_f32_e32 v58, v46, v49
	ds_read_b128 v[208:211], v33 offset:13824
	ds_read_b128 v[212:215], v33 offset:13888
	s_nop 0
	v_readlane_b32 s0, v254, 57
	v_readlane_b32 s1, v254, 58
	s_waitcnt lgkmcnt(3)
	v_mfma_f32_16x16x32_bf16 v[46:49], v[216:219], v[0:3], 0
	s_waitcnt lgkmcnt(2)
	v_mfma_f32_16x16x32_bf16 v[46:49], v[220:223], v[20:23], v[46:49]
	v_fmamk_f32 v50, v28, 0xc2a00000, v27
	v_fmamk_f32 v51, v26, 0x42a00000, v29
	v_cndmask_b32_e64 v50, v51, v50, s[0:1]
	v_exp_f32_e32 v50, v50
	v_readlane_b32 s0, v254, 59
	v_readlane_b32 s1, v254, 60
	s_nop 1
	v_cndmask_b32_e64 v50, v50, 2.0, s[0:1]
	v_readlane_b32 s0, v254, 61
	v_mul_f32_e32 v59, v50, v46
	v_fmamk_f32 v46, v28, 0xc2a20000, v27
	v_fmamk_f32 v50, v26, 0x42a20000, v29
	v_readlane_b32 s1, v254, 62
	s_nop 1
	v_cndmask_b32_e64 v46, v50, v46, s[0:1]
	v_exp_f32_e32 v46, v46
	v_readlane_b32 s0, v254, 63
	v_readlane_b32 s1, v255, 0
	s_nop 1
	v_cndmask_b32_e64 v46, v46, 2.0, s[0:1]
	v_readlane_b32 s0, v255, 1
	v_mul_f32_e32 v60, v46, v47
	v_fmamk_f32 v46, v28, 0xc2a40000, v27
	v_fmamk_f32 v47, v26, 0x42a40000, v29
	v_readlane_b32 s1, v255, 2
	s_nop 1
	v_cndmask_b32_e64 v46, v47, v46, s[0:1]
	v_exp_f32_e32 v46, v46
	v_readlane_b32 s0, v255, 3
	v_readlane_b32 s1, v255, 4
	v_fmamk_f32 v47, v26, 0x42a60000, v29
	s_nop 0
	v_cndmask_b32_e64 v46, v46, 2.0, s[0:1]
	v_readlane_b32 s0, v255, 5
	v_mul_f32_e32 v61, v46, v48
	v_fmamk_f32 v46, v28, 0xc2a60000, v27
	v_readlane_b32 s1, v255, 6
	s_nop 1
	v_cndmask_b32_e64 v46, v47, v46, s[0:1]
	v_exp_f32_e32 v46, v46
	v_readlane_b32 s0, v255, 7
	v_readlane_b32 s1, v255, 8
	s_nop 1
	v_cndmask_b32_e64 v46, v46, 2.0, s[0:1]
	v_mul_f32_e32 v62, v46, v49
	ds_read_b128 v[216:219], v33 offset:16128
	ds_read_b128 v[220:223], v33 offset:16192
	s_nop 0
	v_readlane_b32 s0, v255, 9
	v_readlane_b32 s1, v255, 10
	s_waitcnt lgkmcnt(3)
	v_mfma_f32_16x16x32_bf16 v[46:49], v[208:211], v[0:3], 0
	s_waitcnt lgkmcnt(2)
	v_mfma_f32_16x16x32_bf16 v[46:49], v[212:215], v[20:23], v[46:49]
	v_fmamk_f32 v50, v28, 0xc2c00000, v27
	v_fmamk_f32 v51, v26, 0x42c00000, v29
	v_cndmask_b32_e64 v50, v51, v50, s[0:1]
	v_exp_f32_e32 v50, v50
	v_readlane_b32 s0, v255, 11
	v_readlane_b32 s1, v255, 12
	v_fmamk_f32 v51, v26, 0x42c20000, v29
	s_nop 0
	v_cndmask_b32_e64 v50, v50, 2.0, s[0:1]
	v_readlane_b32 s0, v255, 13
	v_mul_f32_e32 v50, v50, v46
	v_fmamk_f32 v46, v28, 0xc2c20000, v27
	v_readlane_b32 s1, v255, 14
	s_nop 1
	v_cndmask_b32_e64 v46, v51, v46, s[0:1]
	v_exp_f32_e32 v46, v46
	v_readlane_b32 s0, v255, 15
	v_readlane_b32 s1, v255, 16
	s_nop 1
	v_cndmask_b32_e64 v46, v46, 2.0, s[0:1]
	v_readlane_b32 s0, v255, 17
	v_mul_f32_e32 v51, v46, v47
	v_fmamk_f32 v46, v28, 0xc2c40000, v27
	v_fmamk_f32 v47, v26, 0x42c40000, v29
	v_readlane_b32 s1, v255, 18
	s_nop 1
	v_cndmask_b32_e64 v46, v47, v46, s[0:1]
	v_exp_f32_e32 v46, v46
	v_readlane_b32 s0, v255, 19
	v_readlane_b32 s1, v255, 20
	v_fmamk_f32 v47, v26, 0x42c60000, v29
	s_nop 0
	v_cndmask_b32_e64 v46, v46, 2.0, s[0:1]
	v_readlane_b32 s0, v255, 21
	v_mul_f32_e32 v52, v46, v48
	v_fmamk_f32 v46, v28, 0xc2c60000, v27
	v_readlane_b32 s1, v255, 22
	s_nop 1
	v_cndmask_b32_e64 v46, v47, v46, s[0:1]
	v_exp_f32_e32 v46, v46
	v_readlane_b32 s0, v255, 23
	v_readlane_b32 s1, v255, 24
	s_nop 1
	v_cndmask_b32_e64 v46, v46, 2.0, s[0:1]
	v_mul_f32_e32 v53, v46, v49
	s_nop 0
	s_waitcnt lgkmcnt(1)
; __device__ __forceinline__ void m3_outputs(const KQ p_in, int e, bool ctx_full, unsigned char* smem, unsigned* scan_word) {
;     ...
;             for (int mt = 0; mt < 8; ++mt) {
;                 f32x4 a = (f32x4){0.f, 0.f, 0.f, 0.f};
; #pragma unroll
;                 for (int k2 = 0; k2 < 2; ++k2) { const bf16x8 kf = *(const bf16x8*)(Kt + (16 * mt + ln) * 72 + 32 * k2 + 8 * g4); a = __builtin_amdgcn_mfma_f32_16x16x32_bf16(kf, qf[k2], a, 0, 0, 0); }
; #pragma unroll
;                 for (int rg = 0; rg < 4; ++rg) { const int cc = 16 * mt + rg; const int df = di - cc;
;                     const float arg = (df > 0) ? fmaf(-lf2, (float)cc, bfw) : fmaf(lb2, (float)cc, bbw);
;                     float wgt = __builtin_amdgcn_exp2f(arg); wgt = (df == 0) ? 2.0f : wgt;
;                     a[rg] *= wgt; }
;                 st[mt] = a;
;                 __builtin_amdgcn_sched_barrier(0);
;             }
; #pragma unroll
;             for (int ks = 0; ks < 4; ++ks) {
;                 const bf16x8 pfr = pack8(st[2 * ks], st[2 * ks + 1]);
; #pragma unroll
;                 for (int m = 0; m < 4; ++m) {
;                     const int vrow = 16 * m + ln; const int kx = (32 * ks + 4 * g4) ^ (((vrow >> 3) & 7) << 2);
;                     const bf16_t* vr = Vt + vrow * 136;
;                     const bf16x4 v0 = *(const bf16x4*)(vr + kx), v1 = *(const bf16x4*)(vr + (kx ^ 16));
;                     const bf16x8 vf = __builtin_shufflevector(v0, v1, 0, 1, 2, 3, 4, 5, 6, 7);
;                     O[m] = __builtin_amdgcn_mfma_f32_16x16x32_bf16(vf, pfr, O[m], 0, 0, 0);
;                 }
;                 __builtin_amdgcn_sched_barrier(0);
;             }
;             float ss = 0.f;
; #pragma unroll
;             for (int m = 0; m < 4; ++m)
; #pragma unroll
;                 for (int rg = 0; rg < 4; ++rg) ss += O[m][rg] * O[m][rg];
;             ss += __shfl_xor(ss, 16, 64); ss += __shfl_xor(ss, 32, 64);
;             const float rn = rsqrtf(ss * (1.0f / 64.0f) + EPS);
	v_mfma_f32_16x16x32_bf16 v[0:3], v[216:219], v[0:3], 0
	s_nop 0
	s_waitcnt lgkmcnt(0)
	v_mfma_f32_16x16x32_bf16 v[0:3], v[220:223], v[20:23], v[0:3]
	v_fmamk_f32 v20, v28, 0xc2e00000, v27
	v_fmamk_f32 v21, v26, 0x42e00000, v29
	v_cndmask_b32_e64 v20, v21, v20, s[16:17]
	v_exp_f32_e32 v20, v20
	s_nop 0
	v_cndmask_b32_e64 v20, v20, 2.0, s[18:19]
	s_nop 1
	v_mul_f32_e32 v33, v20, v0
	v_fmamk_f32 v0, v28, 0xc2e20000, v27
	v_fmamk_f32 v20, v26, 0x42e20000, v29
	v_cndmask_b32_e64 v0, v20, v0, s[20:21]
	v_exp_f32_e32 v0, v0
	s_nop 0
	v_cndmask_b32_e64 v0, v0, 2.0, s[22:23]
	v_mul_f32_e32 v46, v0, v1
	v_fmamk_f32 v0, v28, 0xc2e40000, v27
	v_fmamk_f32 v1, v26, 0x42e40000, v29
	v_cndmask_b32_e64 v0, v1, v0, s[24:25]
	v_exp_f32_e32 v0, v0
	v_fmac_f32_e32 v27, 0xc2e60000, v28
	v_fmac_f32_e32 v29, 0x42e60000, v26
	v_cndmask_b32_e64 v0, v0, 2.0, s[26:27]
	v_mul_f32_e32 v47, v0, v2
	v_cndmask_b32_e64 v0, v29, v27, s[28:29]
	v_exp_f32_e32 v0, v0
	s_nop 0
	v_cndmask_b32_e64 v0, v0, 2.0, s[30:31]
	v_mul_f32_e32 v26, v0, v3
	v_add_u32_e32 v20, 0x4800, v118
	v_cvt_pk_bf16_f32 v0, v30, v31
	v_cvt_pk_bf16_f32 v1, v32, v34
	v_cvt_pk_bf16_f32 v2, v35, v36
	v_cvt_pk_bf16_f32 v3, v38, v40
	ds_read2_b64 v[20:23], v20 offset1:4
	s_waitcnt lgkmcnt(0)
	v_mfma_f32_16x16x32_bf16 v[4:7], v[20:23], v[0:3], v[4:7]
	v_add_u32_e32 v20, 0x4800, v119
	ds_read2_b64 v[20:23], v20 offset1:4
	s_waitcnt lgkmcnt(0)
	v_mfma_f32_16x16x32_bf16 v[8:11], v[20:23], v[0:3], v[8:11]
	ds_read_b64 v[20:21], v120 offset:18432
	ds_read_b64 v[22:23], v121 offset:18432
	s_waitcnt lgkmcnt(0)
	v_mfma_f32_16x16x32_bf16 v[12:15], v[20:23], v[0:3], v[12:15]
	ds_read_b64 v[20:21], v122 offset:18432
	ds_read_b64 v[22:23], v123 offset:18432
	s_waitcnt lgkmcnt(0)
	v_mfma_f32_16x16x32_bf16 v[0:3], v[20:23], v[0:3], v[16:19]
	v_add_u32_e32 v20, 0x4800, v125
	v_cvt_pk_bf16_f32 v16, v37, v39
	v_cvt_pk_bf16_f32 v17, v41, v42
	v_cvt_pk_bf16_f32 v18, v43, v44
	v_cvt_pk_bf16_f32 v19, v45, v54
	ds_read2_b64 v[20:23], v20 offset1:4
	s_waitcnt lgkmcnt(0)
	v_mfma_f32_16x16x32_bf16 v[4:7], v[20:23], v[16:19], v[4:7]
	v_add_u32_e32 v20, 0x4800, v126
	ds_read2_b64 v[20:23], v20 offset1:4
	s_waitcnt lgkmcnt(0)
	v_mfma_f32_16x16x32_bf16 v[8:11], v[20:23], v[16:19], v[8:11]
	ds_read_b64 v[20:21], v127 offset:18432
	ds_read_b64 v[22:23], v128 offset:18432
	s_waitcnt lgkmcnt(0)
	v_mfma_f32_16x16x32_bf16 v[12:15], v[20:23], v[16:19], v[12:15]
	ds_read_b64 v[20:21], v129 offset:18432
	ds_read_b64 v[22:23], v130 offset:18432
	s_waitcnt lgkmcnt(0)
	v_mfma_f32_16x16x32_bf16 v[0:3], v[20:23], v[16:19], v[0:3]
	v_add_u32_e32 v20, 0x4800, v132
	v_cvt_pk_bf16_f32 v16, v55, v56
	v_cvt_pk_bf16_f32 v17, v57, v58
	v_cvt_pk_bf16_f32 v18, v59, v60
	v_cvt_pk_bf16_f32 v19, v61, v62
	ds_read2_b64 v[20:23], v20 offset1:4
	s_waitcnt lgkmcnt(0)
	v_mfma_f32_16x16x32_bf16 v[4:7], v[20:23], v[16:19], v[4:7]
	v_add_u32_e32 v20, 0x4800, v133
	ds_read2_b64 v[20:23], v20 offset1:4
	s_waitcnt lgkmcnt(0)
	v_mfma_f32_16x16x32_bf16 v[8:11], v[20:23], v[16:19], v[8:11]
	ds_read_b64 v[20:21], v134 offset:18432
	ds_read_b64 v[22:23], v135 offset:18432
	s_waitcnt lgkmcnt(0)
	v_mfma_f32_16x16x32_bf16 v[20:23], v[20:23], v[16:19], v[12:15]
	s_nop 2
	ds_read_b64 v[12:13], v136 offset:18432
	ds_read_b64 v[14:15], v137 offset:18432
	s_waitcnt lgkmcnt(0)
	v_mfma_f32_16x16x32_bf16 v[0:3], v[12:15], v[16:19], v[0:3]
	v_add_u32_e32 v12, 0x4800, v139
	v_cvt_pk_bf16_f32 v16, v50, v51
	v_cvt_pk_bf16_f32 v17, v52, v53
	v_cvt_pk_bf16_f32 v18, v33, v46
	v_cvt_pk_bf16_f32 v19, v47, v26
	ds_read2_b64 v[12:15], v12 offset1:4
	s_waitcnt lgkmcnt(0)
	v_mfma_f32_16x16x32_bf16 v[12:15], v[12:15], v[16:19], v[4:7]
	s_nop 2
	v_add_u32_e32 v4, 0x4800, v140
	ds_read2_b64 v[4:7], v4 offset1:4
	s_waitcnt lgkmcnt(0)
	v_mfma_f32_16x16x32_bf16 v[8:11], v[4:7], v[16:19], v[8:11]
	ds_read_b64 v[4:5], v141 offset:18432
	ds_read_b64 v[6:7], v142 offset:18432
	s_waitcnt lgkmcnt(0)
	v_mfma_f32_16x16x32_bf16 v[4:7], v[4:7], v[16:19], v[20:23]
	s_nop 2
	ds_read_b64 v[20:21], v143 offset:18432
	ds_read_b64 v[22:23], v154 offset:18432
	s_waitcnt lgkmcnt(0)
	v_mfma_f32_16x16x32_bf16 v[0:3], v[20:23], v[16:19], v[0:3]
	v_mul_f32_e32 v20, v13, v13
	v_fmac_f32_e32 v20, v12, v12
	v_fmac_f32_e32 v20, v14, v14
	v_fmac_f32_e32 v20, v15, v15
	v_fmac_f32_e32 v20, v8, v8
	v_fmac_f32_e32 v20, v9, v9
	v_fmac_f32_e32 v20, v10, v10
	v_fmac_f32_e32 v20, v11, v11
	v_pk_mul_f32 v[18:19], v[4:5], v[4:5]
	v_pk_mul_f32 v[16:17], v[6:7], v[6:7]
	v_add_f32_e32 v18, v18, v20
	v_add_f32_e32 v18, v19, v18
	v_add_f32_e32 v16, v16, v18
	v_add_f32_e32 v20, v17, v16
	v_pk_mul_f32 v[18:19], v[0:1], v[0:1]
	v_pk_mul_f32 v[16:17], v[2:3], v[2:3]
	v_add_f32_e32 v18, v18, v20
	v_add_f32_e32 v18, v19, v18
	v_add_f32_e32 v16, v16, v18
	v_and_b32_e32 v18, 64, v205
	v_add_f32_e32 v16, v17, v16
	v_xor_b32_e32 v17, 16, v205
	v_add_u32_e32 v18, 64, v18
	v_cmp_lt_i32_e32 vcc, v17, v18
	v_lshlrev_b32_e32 v20, 1, v86
	v_mov_b32_e32 v21, v145
	v_cndmask_b32_e32 v17, v205, v17, vcc
	v_lshlrev_b32_e32 v17, 2, v17
	ds_bpermute_b32 v17, v17, v16
	s_waitcnt lgkmcnt(0)
	v_add_f32_e32 v16, v16, v17
	v_xor_b32_e32 v17, 32, v205
	v_cmp_lt_i32_e32 vcc, v17, v18
	s_nop 1
	v_cndmask_b32_e32 v17, v205, v17, vcc
	v_lshlrev_b32_e32 v17, 2, v17
	ds_bpermute_b32 v17, v17, v16
	s_waitcnt lgkmcnt(0)
; __device__ __forceinline__ float bf2f(bf16_t b) { return __uint_as_float(((unsigned)b) << 16); }
; __device__ __forceinline__ float silu_f(float x) { return x * __builtin_amdgcn_rcpf(1.0f + __expf(-x)); }
; __device__ __forceinline__ unsigned cvt_pk_bf16(float lo, float hi) { unsigned r; asm volatile("v_cvt_pk_bf16_f32 %0, %1, %2" : "=v"(r) : "v"(lo), "v"(hi)); return r; }
; __device__ __forceinline__ void m3_outputs(const KQ p_in, int e, bool ctx_full, unsigned char* smem, unsigned* scan_word) {
;     ...
;             const float rn = rsqrtf(ss * (1.0f / 64.0f) + EPS);
; #pragma unroll
;             for (int m = 0; m < 4; ++m) {
;                 const int ee = 16 * m + 4 * g4;
;                 const bf16x4 gv = *(const bf16x4*)(Z + (size_t)(t0 + i) * INW + 1024 + h * 64 + ee);
;                 uint2 o2; o2.x = pg8::cvt_pk_bf16(O[m][0] * rn * silu_f(bf2f((bf16_t)gv[0])), O[m][1] * rn * silu_f(bf2f((bf16_t)gv[1])));
;                 o2.y = pg8::cvt_pk_bf16(O[m][2] * rn * silu_f(bf2f((bf16_t)gv[2])), O[m][3] * rn * silu_f(bf2f((bf16_t)gv[3])));
;                 *(uint2*)(MIX + (size_t)(t0 + i) * D + 512 + h * 64 + ee) = o2;
;             }
	v_add_f32_e32 v16, v16, v17
	v_fmamk_f32 v16, v16, 0x3c800000, v146
	v_cmp_gt_f32_e32 vcc, s67, v16
	v_mul_f32_e32 v17, 0x4b800000, v16
	s_nop 0
	v_cndmask_b32_e32 v16, v16, v17, vcc
	v_rsq_f32_e32 v16, v16
	s_nop 0
	v_mul_f32_e32 v17, 0x45800000, v16
	v_cndmask_b32_e32 v26, v16, v17, vcc
	v_lshlrev_b64 v[16:17], 11, v[106:107]
	v_lshl_add_u64 v[16:17], s[90:91], 0, v[16:17]
	v_lshl_add_u64 v[18:19], v[16:17], 0, s[80:81]
	v_lshl_add_u64 v[16:17], v[24:25], 0, v[20:21]
	global_load_dwordx2 v[22:23], v[16:17], off offset:2048
	global_load_dwordx2 v[28:29], v[16:17], off offset:2080
	global_load_dwordx2 v[30:31], v[16:17], off offset:2112
	global_load_dwordx2 v[32:33], v[16:17], off offset:2144
	v_mul_f32_e32 v12, v12, v26
	v_mul_f32_e32 v13, v13, v26
	v_mul_f32_e32 v8, v8, v26
	v_mul_f32_e32 v9, v9, v26
	v_mul_f32_e32 v4, v4, v26
	v_mul_f32_e32 v5, v5, v26
	v_mul_f32_e32 v0, v0, v26
	v_mul_f32_e32 v1, v1, v26
	s_waitcnt lgkmcnt(0)
	s_waitcnt vmcnt(0)
	v_lshlrev_b32_e32 v24, 16, v22
	v_mul_f32_e32 v25, 0xbfb8aa3b, v24
	v_exp_f32_e32 v25, v25
	v_and_b32_e32 v22, 0xffff0000, v22
	v_add_f32_e32 v25, 1.0, v25
	v_rcp_f32_e32 v25, v25
	s_nop 0
	v_mul_f32_e32 v24, v25, v24
	v_mul_f32_e32 v12, v24, v12
	v_mul_f32_e32 v24, 0xbfb8aa3b, v22
	v_exp_f32_e32 v24, v24
	s_nop 0
	v_add_f32_e32 v24, 1.0, v24
	v_rcp_f32_e32 v24, v24
	s_nop 0
	v_mul_f32_e32 v22, v24, v22
	v_mul_f32_e32 v13, v22, v13
	v_cvt_pk_bf16_f32 v22, v12, v13
	v_lshlrev_b32_e32 v13, 16, v23
	v_mul_f32_e32 v12, v14, v26
	v_mul_f32_e32 v14, 0xbfb8aa3b, v13
	v_exp_f32_e32 v14, v14
	s_nop 0
	v_add_f32_e32 v14, 1.0, v14
	v_rcp_f32_e32 v14, v14
	s_nop 0
	v_mul_f32_e32 v13, v14, v13
	v_and_b32_e32 v14, 0xffff0000, v23
	v_mul_f32_e32 v12, v13, v12
	v_mul_f32_e32 v13, v15, v26
	v_mul_f32_e32 v15, 0xbfb8aa3b, v14
	v_exp_f32_e32 v15, v15
	s_nop 0
	v_add_f32_e32 v15, 1.0, v15
	v_rcp_f32_e32 v15, v15
	s_nop 0
	v_mul_f32_e32 v14, v15, v14
	v_mul_f32_e32 v13, v14, v13
	v_cvt_pk_bf16_f32 v23, v12, v13
	v_mov_b32_e32 v14, v28
	v_mov_b32_e32 v15, v29
	v_lshl_add_u64 v[12:13], v[18:19], 0, v[20:21]
	global_store_dwordx2 v[12:13], v[22:23], off offset:1024
	s_waitcnt lgkmcnt(0)
	s_waitcnt vmcnt(1)
	v_lshlrev_b32_e32 v18, 16, v14
	v_mul_f32_e32 v19, 0xbfb8aa3b, v18
	v_exp_f32_e32 v19, v19
	v_and_b32_e32 v14, 0xffff0000, v14
	v_add_f32_e32 v19, 1.0, v19
	v_rcp_f32_e32 v19, v19
	s_nop 0
	v_mul_f32_e32 v18, v19, v18
	v_mul_f32_e32 v8, v8, v18
	v_mul_f32_e32 v18, 0xbfb8aa3b, v14
	v_exp_f32_e32 v18, v18
	s_nop 0
	v_add_f32_e32 v18, 1.0, v18
	v_rcp_f32_e32 v18, v18
	s_nop 0
	v_mul_f32_e32 v14, v18, v14
	v_mul_f32_e32 v9, v9, v14
	v_cvt_pk_bf16_f32 v8, v8, v9
	v_mul_f32_e32 v9, v10, v26
	v_lshlrev_b32_e32 v10, 16, v15
	v_mul_f32_e32 v14, 0xbfb8aa3b, v10
	v_exp_f32_e32 v14, v14
	s_nop 0
	v_add_f32_e32 v14, 1.0, v14
	v_rcp_f32_e32 v14, v14
	s_nop 0
	v_mul_f32_e32 v10, v14, v10
	v_mul_f32_e32 v9, v9, v10
	v_mul_f32_e32 v10, v11, v26
	v_and_b32_e32 v11, 0xffff0000, v15
	v_mul_f32_e32 v14, 0xbfb8aa3b, v11
	v_exp_f32_e32 v14, v14
	s_nop 0
	v_add_f32_e32 v14, 1.0, v14
	v_rcp_f32_e32 v14, v14
	s_nop 0
	v_mul_f32_e32 v11, v14, v11
	v_mul_f32_e32 v10, v10, v11
	v_cvt_pk_bf16_f32 v9, v9, v10
	global_store_dwordx2 v[12:13], v[8:9], off offset:1056
	v_mov_b32_e32 v8, v30
	v_mov_b32_e32 v9, v31
	s_waitcnt lgkmcnt(0)
	s_waitcnt vmcnt(0)
	v_lshlrev_b32_e32 v10, 16, v8
	v_mul_f32_e32 v11, 0xbfb8aa3b, v10
	v_exp_f32_e32 v11, v11
	v_and_b32_e32 v8, 0xffff0000, v8
	v_add_f32_e32 v11, 1.0, v11
	v_rcp_f32_e32 v11, v11
	s_nop 0
	v_mul_f32_e32 v10, v11, v10
	v_mul_f32_e32 v4, v4, v10
	v_mul_f32_e32 v10, 0xbfb8aa3b, v8
	v_exp_f32_e32 v10, v10
	s_nop 0
	v_add_f32_e32 v10, 1.0, v10
	v_rcp_f32_e32 v10, v10
	s_nop 0
	v_mul_f32_e32 v8, v10, v8
	v_mul_f32_e32 v5, v5, v8
	v_cvt_pk_bf16_f32 v4, v4, v5
	v_mul_f32_e32 v5, v6, v26
	v_lshlrev_b32_e32 v6, 16, v9
	v_mul_f32_e32 v8, 0xbfb8aa3b, v6
	v_exp_f32_e32 v8, v8
	s_nop 0
	v_add_f32_e32 v8, 1.0, v8
	v_rcp_f32_e32 v8, v8
	s_nop 0
	v_mul_f32_e32 v6, v8, v6
	v_mul_f32_e32 v5, v5, v6
	v_mul_f32_e32 v6, v7, v26
	v_and_b32_e32 v7, 0xffff0000, v9
	v_mul_f32_e32 v8, 0xbfb8aa3b, v7
	v_exp_f32_e32 v8, v8
	s_nop 0
	v_add_f32_e32 v8, 1.0, v8
	v_rcp_f32_e32 v8, v8
	s_nop 0
	v_mul_f32_e32 v7, v8, v7
	v_mul_f32_e32 v6, v6, v7
	v_cvt_pk_bf16_f32 v5, v5, v6
	global_store_dwordx2 v[12:13], v[4:5], off offset:1088
	v_mov_b32_e32 v4, v32
	v_mov_b32_e32 v5, v33
	s_waitcnt lgkmcnt(0)
	s_waitcnt vmcnt(0)
	v_lshlrev_b32_e32 v6, 16, v4
	v_mul_f32_e32 v7, 0xbfb8aa3b, v6
	v_exp_f32_e32 v7, v7
	v_and_b32_e32 v4, 0xffff0000, v4
	v_add_f32_e32 v7, 1.0, v7
	v_rcp_f32_e32 v7, v7
	s_nop 0
	v_mul_f32_e32 v6, v7, v6
	v_mul_f32_e32 v0, v0, v6
	v_mul_f32_e32 v6, 0xbfb8aa3b, v4
	v_exp_f32_e32 v6, v6
	s_nop 0
	v_add_f32_e32 v6, 1.0, v6
	v_rcp_f32_e32 v6, v6
	s_nop 0
	v_mul_f32_e32 v4, v6, v4
	v_mul_f32_e32 v1, v1, v4
	v_cvt_pk_bf16_f32 v0, v0, v1
	v_mul_f32_e32 v1, v2, v26
	v_lshlrev_b32_e32 v2, 16, v5
	v_mul_f32_e32 v4, 0xbfb8aa3b, v2
	v_exp_f32_e32 v4, v4
	s_nop 0
	v_add_f32_e32 v4, 1.0, v4
	v_rcp_f32_e32 v4, v4
	s_nop 0
	v_mul_f32_e32 v2, v4, v2
	v_mul_f32_e32 v1, v1, v2
	v_mul_f32_e32 v2, v3, v26
	v_and_b32_e32 v3, 0xffff0000, v5
	v_mul_f32_e32 v4, 0xbfb8aa3b, v3
	v_exp_f32_e32 v4, v4
	s_nop 0
	v_add_f32_e32 v4, 1.0, v4
	v_rcp_f32_e32 v4, v4
	s_nop 0
	v_mul_f32_e32 v3, v4, v3
	v_mul_f32_e32 v2, v2, v3
	v_cvt_pk_bf16_f32 v1, v1, v2
	global_store_dwordx2 v[12:13], v[0:1], off offset:1120
	s_cbranch_execnz .LBB0_933
	s_branch .LBB0_963

; __device__ __forceinline__ void m3_outputs(const KQ p_in, int e, bool ctx_full, unsigned char* smem, unsigned* scan_word) {
;     ...
;                 for (int mt = 0; mt < 8; ++mt) {
;                     f32x4 a = (f32x4){0.f, 0.f, 0.f, 0.f};
; #pragma unroll
;                     for (int k2 = 0; k2 < 2; ++k2) { const bf16x8 kf = *(const bf16x8*)(Kt + (16 * mt + ln) * 72 + 32 * k2 + 8 * g4); a = __builtin_amdgcn_mfma_f32_16x16x32_bf16(kf, qf[k2], a, 0, 0, 0); }
;                     if (!isc && tl != 1) {
; #pragma unroll
;                         for (int rg = 0; rg < 4; ++rg) { const int dd = qpos - (kp0 + 16 * mt + 4 * g4 + rg); if (dd > 128 || dd < -128) a[rg] = -1e30f; }
;                     }
; #pragma unroll
;                     for (int rg = 0; rg < 4; ++rg) mloc = fmaxf(mloc, a[rg]);
;                     st[mt] = a;
;                     __builtin_amdgcn_sched_barrier(0);
;                 }
.LBB0_976:
	v_add_u32_e32 v69, v111, v117
	ds_read_b128 v[208:211], v69
	ds_read_b128 v[212:215], v69 offset:64
	ds_read_b128 v[216:219], v69 offset:2304
	ds_read_b128 v[220:223], v69 offset:2368
	s_nop 0
	s_add_i32 s0, s13, s8
	s_lshl_b32 s0, s0, 7
	s_sub_i32 s6, 0x80, s0
	s_cmp_lt_i32 s13, 3
	s_cselect_b64 s[0:1], -1, 0
	s_cmp_lg_u32 s13, 1
	s_cselect_b64 s[4:5], -1, 0
	s_waitcnt lgkmcnt(2)
	v_mfma_f32_16x16x32_bf16 v[40:43], v[208:211], v[0:3], 0
	s_and_b64 s[0:1], s[0:1], s[4:5]
	v_add_u32_e32 v71, s6, v149
	s_andn2_b64 vcc, exec, s[0:1]
	v_mfma_f32_16x16x32_bf16 v[40:43], v[212:215], v[4:7], v[40:43]
	v_cndmask_b32_e64 v44, 0, 1, s[0:1]
	v_cmp_ne_u32_e64 s[36:37], 1, v44
	v_sub_u32_e32 v70, v71, v86
	s_cbranch_vccnz .LBB0_978
	v_mov_b32_e32 v44, s60
	v_cmp_gt_u32_e32 vcc, s58, v70
	s_movk_i32 s0, 0x101
	s_nop 0
	v_cndmask_b32_e32 v40, v40, v44, vcc
	v_sub_u32_e32 v44, v86, v71
	v_cmp_gt_u32_e32 vcc, s0, v44
	v_add_u32_e32 v44, -2, v70
	s_nop 0
	v_cndmask_b32_e32 v41, v207, v41, vcc
	v_cmp_lt_u32_e32 vcc, s61, v44
	v_add_u32_e32 v44, -3, v70
	s_nop 0
	v_cndmask_b32_e32 v42, v207, v42, vcc
	v_cmp_lt_u32_e32 vcc, s61, v44
	s_nop 1
	v_cndmask_b32_e32 v43, v207, v43, vcc
.LBB0_978:
	ds_read_b128 v[208:211], v69 offset:4608
	ds_read_b128 v[212:215], v69 offset:4672
	s_nop 0
	s_and_b64 vcc, exec, s[36:37]
	s_waitcnt lgkmcnt(2)
	v_mfma_f32_16x16x32_bf16 v[44:47], v[216:219], v[0:3], 0
	v_mfma_f32_16x16x32_bf16 v[44:47], v[220:223], v[4:7], v[44:47]
	s_cbranch_vccnz .LBB0_980
	v_sub_u32_e32 v48, v71, v155
	v_cmp_gt_u32_e32 vcc, s58, v48
	v_mov_b32_e32 v48, s60
	s_nop 3
	v_cndmask_b32_e32 v44, v44, v48, vcc
	v_subrev_u32_e32 v48, 17, v70
	v_cmp_lt_u32_e32 vcc, s61, v48
	v_subrev_u32_e32 v48, 18, v70
	s_nop 0
	v_cndmask_b32_e32 v45, v207, v45, vcc
	v_cmp_lt_u32_e32 vcc, s61, v48
	v_subrev_u32_e32 v48, 19, v70
	s_nop 0
	v_cndmask_b32_e32 v46, v207, v46, vcc
	v_cmp_lt_u32_e32 vcc, s61, v48
	s_nop 1
	v_cndmask_b32_e32 v47, v207, v47, vcc
.LBB0_980:
	ds_read_b128 v[216:219], v69 offset:6912
	ds_read_b128 v[220:223], v69 offset:6976
	s_nop 0
	s_and_b64 vcc, exec, s[36:37]
	s_waitcnt lgkmcnt(2)
	v_mfma_f32_16x16x32_bf16 v[48:51], v[208:211], v[0:3], 0
	v_mfma_f32_16x16x32_bf16 v[48:51], v[212:215], v[4:7], v[48:51]
	s_cbranch_vccnz .LBB0_982
	v_sub_u32_e32 v52, v71, v124
	v_cmp_gt_u32_e32 vcc, s58, v52
	v_mov_b32_e32 v52, s60
	s_nop 3
	v_cndmask_b32_e32 v48, v48, v52, vcc
	v_subrev_u32_e32 v52, 33, v70
	v_cmp_lt_u32_e32 vcc, s61, v52
	v_subrev_u32_e32 v52, 34, v70
	s_nop 0
	v_cndmask_b32_e32 v49, v207, v49, vcc
	v_cmp_lt_u32_e32 vcc, s61, v52
	v_subrev_u32_e32 v52, 35, v70
	s_nop 0
	v_cndmask_b32_e32 v50, v207, v50, vcc
	v_cmp_lt_u32_e32 vcc, s61, v52
	s_nop 1
	v_cndmask_b32_e32 v51, v207, v51, vcc
.LBB0_982:
	ds_read_b128 v[208:211], v69 offset:9216
	ds_read_b128 v[212:215], v69 offset:9280
	s_nop 0
	s_and_b64 vcc, exec, s[36:37]
	s_waitcnt lgkmcnt(2)
	v_mfma_f32_16x16x32_bf16 v[52:55], v[216:219], v[0:3], 0
	v_mfma_f32_16x16x32_bf16 v[52:55], v[220:223], v[4:7], v[52:55]
	s_cbranch_vccnz .LBB0_984
	v_sub_u32_e32 v56, v71, v156
	v_cmp_gt_u32_e32 vcc, s58, v56
	v_mov_b32_e32 v56, s60
	s_nop 3
	v_cndmask_b32_e32 v52, v52, v56, vcc
	v_subrev_u32_e32 v56, 49, v70
	v_cmp_lt_u32_e32 vcc, s61, v56
	v_subrev_u32_e32 v56, 50, v70
	s_nop 0
	v_cndmask_b32_e32 v53, v207, v53, vcc
	v_cmp_lt_u32_e32 vcc, s61, v56
	v_subrev_u32_e32 v56, 51, v70
	s_nop 0
	v_cndmask_b32_e32 v54, v207, v54, vcc
	v_cmp_lt_u32_e32 vcc, s61, v56
	s_nop 1
	v_cndmask_b32_e32 v55, v207, v55, vcc
.LBB0_984:
	ds_read_b128 v[216:219], v69 offset:11520
	ds_read_b128 v[220:223], v69 offset:11584
	s_nop 0
	s_and_b64 vcc, exec, s[36:37]
	s_waitcnt lgkmcnt(2)
	v_mfma_f32_16x16x32_bf16 v[56:59], v[208:211], v[0:3], 0
	v_mfma_f32_16x16x32_bf16 v[56:59], v[212:215], v[4:7], v[56:59]
	s_cbranch_vccnz .LBB0_986
	v_sub_u32_e32 v60, v71, v131
	v_cmp_gt_u32_e32 vcc, s58, v60
	v_mov_b32_e32 v60, s60
	s_nop 3
	v_cndmask_b32_e32 v56, v56, v60, vcc
	v_add_u32_e32 v60, 0xffffffbf, v70
	v_cmp_lt_u32_e32 vcc, s61, v60
	v_add_u32_e32 v60, 0xffffffbe, v70
	s_nop 0
	v_cndmask_b32_e32 v57, v207, v57, vcc
	v_cmp_lt_u32_e32 vcc, s61, v60
	v_add_u32_e32 v60, 0xffffffbd, v70
	s_nop 0
	v_cndmask_b32_e32 v58, v207, v58, vcc
	v_cmp_lt_u32_e32 vcc, s61, v60
	s_nop 1
	v_cndmask_b32_e32 v59, v207, v59, vcc
.LBB0_986:
	ds_read_b128 v[208:211], v69 offset:13824
	ds_read_b128 v[212:215], v69 offset:13888
	s_nop 0
	s_and_b64 vcc, exec, s[36:37]
	s_waitcnt lgkmcnt(2)
	v_mfma_f32_16x16x32_bf16 v[60:63], v[216:219], v[0:3], 0
	v_mfma_f32_16x16x32_bf16 v[60:63], v[220:223], v[4:7], v[60:63]
	s_cbranch_vccnz .LBB0_988
	v_add_u32_e32 v64, 0xffffffb0, v70
	v_cmp_gt_u32_e32 vcc, s58, v64
	v_mov_b32_e32 v64, s60
	s_nop 3
	v_cndmask_b32_e32 v60, v60, v64, vcc
	v_add_u32_e32 v64, 0xffffffaf, v70
	v_cmp_lt_u32_e32 vcc, s61, v64
	v_add_u32_e32 v64, 0xffffffae, v70
	s_nop 0
	v_cndmask_b32_e32 v61, v207, v61, vcc
	v_cmp_lt_u32_e32 vcc, s61, v64
	v_add_u32_e32 v64, 0xffffffad, v70
	s_nop 0
	v_cndmask_b32_e32 v62, v207, v62, vcc
	v_cmp_lt_u32_e32 vcc, s61, v64
	s_nop 1
	v_cndmask_b32_e32 v63, v207, v63, vcc
.LBB0_988:
	ds_read_b128 v[216:219], v69 offset:16128
	ds_read_b128 v[220:223], v69 offset:16192
	s_nop 0
	s_and_b64 vcc, exec, s[36:37]
	s_waitcnt lgkmcnt(2)
	v_mfma_f32_16x16x32_bf16 v[64:67], v[208:211], v[0:3], 0
	v_mfma_f32_16x16x32_bf16 v[64:67], v[212:215], v[4:7], v[64:67]
	s_cbranch_vccnz .LBB0_990
	v_sub_u32_e32 v71, v71, v138
	v_mov_b32_e32 v72, s60
	v_cmp_gt_u32_e32 vcc, s58, v71
	v_add_u32_e32 v71, 0xffffff9f, v70
	s_nop 2
	v_cndmask_b32_e32 v64, v64, v72, vcc
	v_cmp_lt_u32_e32 vcc, s61, v71
	v_add_u32_e32 v71, 0xffffff9e, v70
	s_nop 0
	v_cndmask_b32_e32 v65, v207, v65, vcc
	v_cmp_lt_u32_e32 vcc, s61, v71
	v_add_u32_e32 v71, 0xffffff9d, v70
	s_nop 0
	v_cndmask_b32_e32 v66, v207, v66, vcc
	v_cmp_lt_u32_e32 vcc, s61, v71
	s_nop 1
	v_cndmask_b32_e32 v67, v207, v67, vcc
.LBB0_990:
	s_nop 0
	s_nop 0
	s_and_b64 vcc, exec, s[36:37]
	s_waitcnt lgkmcnt(0)
	v_mfma_f32_16x16x32_bf16 v[72:75], v[216:219], v[0:3], 0
	v_mfma_f32_16x16x32_bf16 v[72:75], v[220:223], v[4:7], v[72:75]
	s_cbranch_vccnz .LBB0_992
	v_add_u32_e32 v69, 0xffffff90, v70
	v_cmp_gt_u32_e32 vcc, s58, v69
	v_mov_b32_e32 v76, s60
	v_add_u32_e32 v69, 0xffffff8f, v70
	s_nop 2
	v_cndmask_b32_e32 v72, v72, v76, vcc
	v_cmp_lt_u32_e32 vcc, s61, v69
	v_add_u32_e32 v69, 0xffffff8e, v70
	s_nop 0
	v_cndmask_b32_e32 v73, v207, v73, vcc
	v_cmp_lt_u32_e32 vcc, s61, v69
	v_add_u32_e32 v69, 0xffffff8d, v70
	s_nop 0
	v_cndmask_b32_e32 v74, v207, v74, vcc
	v_cmp_lt_u32_e32 vcc, s61, v69
	s_nop 1
	v_cndmask_b32_e32 v75, v207, v75, vcc
